# v31 plus mid compress-GEMM-1 K loop: LDS fragment reads software-pipelined (A ring of 3, B rings of 2) instead of read-wait-MFMA serialisation
# speedup vs baseline: 1.0028x; 1.0028x over previous
.LBB0_1079:
	s_addk_i32 s26, 0x80
	s_setprio 1
	ds_read_b128 v[172:175], v163
	ds_read_b128 v[176:179], v165 offset:16384
	ds_read_b128 v[180:183], v165 offset:20480
	s_waitcnt lgkmcnt(1)
	v_mfma_f32_32x32x16_bf16 v[52:67], v[172:175], v[176:179], v[52:67]
	ds_read_b128 v[194:197], v163 offset:4096
	s_waitcnt lgkmcnt(1)
	v_mfma_f32_32x32x16_bf16 v[36:51], v[172:175], v[180:183], v[36:51]
	ds_read_b128 v[198:201], v166
	ds_read_b128 v[202:205], v167 offset:16384
	s_waitcnt lgkmcnt(2)
	v_mfma_f32_32x32x16_bf16 v[20:35], v[194:197], v[176:179], v[20:35]
	ds_read_b128 v[222:225], v167 offset:20480
	v_mfma_f32_32x32x16_bf16 v[4:19], v[194:197], v[180:183], v[4:19]
	s_waitcnt lgkmcnt(1)
	v_mfma_f32_32x32x16_bf16 v[52:67], v[198:201], v[202:205], v[52:67]
	ds_read_b128 v[172:175], v166 offset:4096
	s_waitcnt lgkmcnt(1)
	v_mfma_f32_32x32x16_bf16 v[36:51], v[198:201], v[222:225], v[36:51]
	ds_read_b128 v[194:197], v168
	ds_read_b128 v[176:179], v169 offset:16384
	s_waitcnt lgkmcnt(2)
	v_mfma_f32_32x32x16_bf16 v[20:35], v[172:175], v[202:205], v[20:35]
	ds_read_b128 v[180:183], v169 offset:20480
	v_mfma_f32_32x32x16_bf16 v[4:19], v[172:175], v[222:225], v[4:19]
	s_waitcnt lgkmcnt(1)
	v_mfma_f32_32x32x16_bf16 v[52:67], v[194:197], v[176:179], v[52:67]
	ds_read_b128 v[198:201], v168 offset:4096
	s_waitcnt lgkmcnt(1)
	v_mfma_f32_32x32x16_bf16 v[36:51], v[194:197], v[180:183], v[36:51]
	ds_read_b128 v[172:175], v170
	ds_read_b128 v[202:205], v171 offset:16384
	s_waitcnt lgkmcnt(2)
	v_mfma_f32_32x32x16_bf16 v[20:35], v[198:201], v[176:179], v[20:35]
	ds_read_b128 v[222:225], v171 offset:20480
	v_mfma_f32_32x32x16_bf16 v[4:19], v[198:201], v[180:183], v[4:19]
	s_waitcnt lgkmcnt(1)
	v_mfma_f32_32x32x16_bf16 v[52:67], v[172:175], v[202:205], v[52:67]
	ds_read_b128 v[194:197], v170 offset:4096
	s_waitcnt lgkmcnt(1)
	v_mfma_f32_32x32x16_bf16 v[36:51], v[172:175], v[222:225], v[36:51]
	s_waitcnt lgkmcnt(0)
	v_mfma_f32_32x32x16_bf16 v[20:35], v[194:197], v[202:205], v[20:35]
	v_mfma_f32_32x32x16_bf16 v[4:19], v[194:197], v[222:225], v[4:19]
	s_setprio 0
	v_lshl_add_u64 v[140:141], v[140:141], 0, s[82:83]
	v_lshl_add_u64 v[142:143], v[142:143], 0, s[82:83]
	v_lshl_add_u64 v[144:145], v[144:145], 0, s[82:83]
	v_lshl_add_u64 v[146:147], v[146:147], 0, s[82:83]
	v_lshl_add_u64 v[148:149], v[148:149], 0, s[82:83]
	v_lshl_add_u64 v[150:151], v[150:151], 0, s[82:83]
	v_lshl_add_u64 v[152:153], v[152:153], 0, s[82:83]
	s_andn2_b64 vcc, exec, s[2:3]
	v_lshl_add_u64 v[154:155], v[154:155], 0, s[82:83]
	s_barrier
	s_cbranch_vccz .LBB0_1099

.LBB0_1090:
	s_setprio 1
	ds_read_b128 v[172:175], v163
	ds_read_b128 v[176:179], v165 offset:16384
	ds_read_b128 v[180:183], v165 offset:20480
	s_waitcnt lgkmcnt(1)
	v_mfma_f32_32x32x16_bf16 v[52:67], v[172:175], v[176:179], v[52:67]
	ds_read_b128 v[194:197], v163 offset:4096
	s_waitcnt lgkmcnt(1)
	v_mfma_f32_32x32x16_bf16 v[36:51], v[172:175], v[180:183], v[36:51]
	ds_read_b128 v[198:201], v166
	ds_read_b128 v[202:205], v167 offset:16384
	s_waitcnt lgkmcnt(2)
	v_mfma_f32_32x32x16_bf16 v[20:35], v[194:197], v[176:179], v[20:35]
	ds_read_b128 v[222:225], v167 offset:20480
	v_mfma_f32_32x32x16_bf16 v[4:19], v[194:197], v[180:183], v[4:19]
	s_waitcnt lgkmcnt(1)
	v_mfma_f32_32x32x16_bf16 v[52:67], v[198:201], v[202:205], v[52:67]
	ds_read_b128 v[172:175], v166 offset:4096
	s_waitcnt lgkmcnt(1)
	v_mfma_f32_32x32x16_bf16 v[36:51], v[198:201], v[222:225], v[36:51]
	ds_read_b128 v[194:197], v168
	ds_read_b128 v[176:179], v169 offset:16384
	s_waitcnt lgkmcnt(2)
	v_mfma_f32_32x32x16_bf16 v[20:35], v[172:175], v[202:205], v[20:35]
	ds_read_b128 v[180:183], v169 offset:20480
	v_mfma_f32_32x32x16_bf16 v[4:19], v[172:175], v[222:225], v[4:19]
	s_waitcnt lgkmcnt(1)
	v_mfma_f32_32x32x16_bf16 v[52:67], v[194:197], v[176:179], v[52:67]
	ds_read_b128 v[198:201], v168 offset:4096
	s_waitcnt lgkmcnt(1)
	v_mfma_f32_32x32x16_bf16 v[36:51], v[194:197], v[180:183], v[36:51]
	ds_read_b128 v[172:175], v170
	ds_read_b128 v[202:205], v171 offset:16384
	s_waitcnt lgkmcnt(2)
	v_mfma_f32_32x32x16_bf16 v[20:35], v[198:201], v[176:179], v[20:35]
	ds_read_b128 v[222:225], v171 offset:20480
	v_mfma_f32_32x32x16_bf16 v[4:19], v[198:201], v[180:183], v[4:19]
	s_waitcnt lgkmcnt(1)
	v_mfma_f32_32x32x16_bf16 v[52:67], v[172:175], v[202:205], v[52:67]
	ds_read_b128 v[194:197], v170 offset:4096
	s_waitcnt lgkmcnt(1)
	v_mfma_f32_32x32x16_bf16 v[36:51], v[172:175], v[222:225], v[36:51]
	s_waitcnt lgkmcnt(0)
	v_mfma_f32_32x32x16_bf16 v[20:35], v[194:197], v[202:205], v[20:35]
	v_mfma_f32_32x32x16_bf16 v[4:19], v[194:197], v[222:225], v[4:19]
	s_setprio 0
	s_cmpk_gt_u32 s26, 0xf3f
	s_barrier
	ds_write_b128 v164, v[84:87]
	s_waitcnt vmcnt(3)
	ds_write_b128 v164, v[96:99] offset:16384
	ds_write_b128 v164, v[92:95] offset:4096
	s_waitcnt vmcnt(2)
	ds_write_b128 v164, v[108:111] offset:20480
	ds_write_b128 v164, v[116:119] offset:8192
	s_waitcnt vmcnt(1)
	ds_write_b128 v164, v[120:123] offset:24576
	ds_write_b128 v164, v[124:127] offset:12288
	s_waitcnt vmcnt(0)
	ds_write_b128 v164, v[128:131] offset:28672
	s_waitcnt lgkmcnt(0)
	s_barrier
	s_cbranch_scc1 .LBB0_1079
	v_mov_b32_e32 v92, v0
	v_mov_b32_e32 v93, v0
	v_mov_b32_e32 v94, v0
	v_mov_b32_e32 v95, v0
	v_mov_b64_e32 v[84:85], v[92:93]
	v_mov_b64_e32 v[86:87], v[94:95]
	s_and_saveexec_b64 s[4:5], s[6:7]
	s_cbranch_execz .LBB0_1093
	v_lshl_add_u64 v[2:3], v[146:147], 0, v[138:139]
	v_add_co_u32_e32 v2, vcc, 0x11dd8000, v2
	s_nop 1
	v_addc_co_u32_e32 v3, vcc, 0, v3, vcc
	global_load_dwordx4 v[84:87], v[2:3], off offset:2432
